# prologue gain-folded transposes now issue all 32 weights + 32 gains of an item before one wait
# speedup vs baseline: 1.0080x; 1.0047x over previous
; #define LAS __attribute__((address_space(3)))
; __device__ __forceinline__ void transpose_item(const float* W, int N, int k0, int n0, bf16_t* dst, int ldd, LAS float* scr, int lane, const float* gk = nullptr) {
; #pragma unroll 8
;     for (int i = 0; i < 32; ++i) { const int kk = 2 * i + (lane >> 5); scr[kk * 33 + (lane & 31)] = W[(size_t)(k0 + kk) * N + n0 + (lane & 31)] * (gk ? gk[k0 + kk] : 1.0f); }
;     asm volatile("s_waitcnt lgkmcnt(0)" ::: "memory");
; __global__ void __launch_bounds__(512, 2) fwd_mega(Args args) {
;     ...
;             if (r < I_UP) { const int kb = r / 176, nb = r % 176, n0 = 32 * nb; const int bj = n0 / DFF, ch = n0 % DFF; const int drow = (ch >> 7) * 256 + bj * 128 + (ch & 127);
;                 transpose_item(w_up + (size_t)l * DM * UPW, UPW, 64 * kb, n0, (bf16_t*)(wl + W_UP) + (size_t)drow * 1024, 1024, scr, lane, ln2 + (size_t)l * DM); continue; }
.LBB0_19:
.LBB0_20:
	v_lshl_add_u64 v[160:161], v[40:41], 0, s[16:17]
	global_load_dword v96, v[160:161], off
	v_lshl_add_u64 v[160:161], v[38:39], 0, s[16:17]
	global_load_dword v97, v[160:161], off
	v_lshl_add_u64 v[160:161], v[36:37], 0, s[16:17]
	global_load_dword v98, v[160:161], off
	v_lshl_add_u64 v[160:161], v[34:35], 0, s[16:17]
	global_load_dword v99, v[160:161], off
	v_lshl_add_u64 v[160:161], v[32:33], 0, s[16:17]
	global_load_dword v100, v[160:161], off
	v_lshl_add_u64 v[160:161], v[30:31], 0, s[16:17]
	global_load_dword v101, v[160:161], off
	v_lshl_add_u64 v[160:161], v[28:29], 0, s[16:17]
	global_load_dword v102, v[160:161], off
	v_lshl_add_u64 v[160:161], v[24:25], 0, s[16:17]
	global_load_dword v103, v[160:161], off
	s_add_u32 s98, s16, 0x58000
	s_addc_u32 s99, s17, 0
	v_lshl_add_u64 v[160:161], v[40:41], 0, s[98:99]
	global_load_dword v104, v[160:161], off
	v_lshl_add_u64 v[160:161], v[38:39], 0, s[98:99]
	global_load_dword v105, v[160:161], off
	v_lshl_add_u64 v[160:161], v[36:37], 0, s[98:99]
	global_load_dword v106, v[160:161], off
	v_lshl_add_u64 v[160:161], v[34:35], 0, s[98:99]
	global_load_dword v107, v[160:161], off
	v_lshl_add_u64 v[160:161], v[32:33], 0, s[98:99]
	global_load_dword v108, v[160:161], off
	v_lshl_add_u64 v[160:161], v[30:31], 0, s[98:99]
	global_load_dword v109, v[160:161], off
	v_lshl_add_u64 v[160:161], v[28:29], 0, s[98:99]
	global_load_dword v110, v[160:161], off
	v_lshl_add_u64 v[160:161], v[24:25], 0, s[98:99]
	global_load_dword v111, v[160:161], off
	s_add_u32 s98, s16, 0xb0000
	s_addc_u32 s99, s17, 0
	v_lshl_add_u64 v[160:161], v[40:41], 0, s[98:99]
	global_load_dword v112, v[160:161], off
	v_lshl_add_u64 v[160:161], v[38:39], 0, s[98:99]
	global_load_dword v113, v[160:161], off
	v_lshl_add_u64 v[160:161], v[36:37], 0, s[98:99]
	global_load_dword v114, v[160:161], off
	v_lshl_add_u64 v[160:161], v[34:35], 0, s[98:99]
	global_load_dword v115, v[160:161], off
	v_lshl_add_u64 v[160:161], v[32:33], 0, s[98:99]
	global_load_dword v116, v[160:161], off
	v_lshl_add_u64 v[160:161], v[30:31], 0, s[98:99]
	global_load_dword v117, v[160:161], off
	v_lshl_add_u64 v[160:161], v[28:29], 0, s[98:99]
	global_load_dword v118, v[160:161], off
	v_lshl_add_u64 v[160:161], v[24:25], 0, s[98:99]
	global_load_dword v119, v[160:161], off
	s_add_u32 s98, s16, 0x108000
	s_addc_u32 s99, s17, 0
	v_lshl_add_u64 v[160:161], v[40:41], 0, s[98:99]
	global_load_dword v120, v[160:161], off
	v_lshl_add_u64 v[160:161], v[38:39], 0, s[98:99]
	global_load_dword v121, v[160:161], off
	v_lshl_add_u64 v[160:161], v[36:37], 0, s[98:99]
	global_load_dword v122, v[160:161], off
	v_lshl_add_u64 v[160:161], v[34:35], 0, s[98:99]
	global_load_dword v123, v[160:161], off
	v_lshl_add_u64 v[160:161], v[32:33], 0, s[98:99]
	global_load_dword v124, v[160:161], off
	v_lshl_add_u64 v[160:161], v[30:31], 0, s[98:99]
	global_load_dword v125, v[160:161], off
	v_lshl_add_u64 v[160:161], v[28:29], 0, s[98:99]
	global_load_dword v126, v[160:161], off
	v_lshl_add_u64 v[160:161], v[24:25], 0, s[98:99]
	global_load_dword v127, v[160:161], off
	v_mov_b32_e32 v128, 1.0
	v_mov_b32_e32 v129, 1.0
	v_mov_b32_e32 v130, 1.0
	v_mov_b32_e32 v131, 1.0
	v_mov_b32_e32 v132, 1.0
	v_mov_b32_e32 v133, 1.0
	v_mov_b32_e32 v134, 1.0
	v_mov_b32_e32 v135, 1.0
	v_mov_b32_e32 v136, 1.0
	v_mov_b32_e32 v137, 1.0
	v_mov_b32_e32 v138, 1.0
	v_mov_b32_e32 v139, 1.0
	v_mov_b32_e32 v140, 1.0
	v_mov_b32_e32 v141, 1.0
	v_mov_b32_e32 v142, 1.0
	v_mov_b32_e32 v143, 1.0
	v_mov_b32_e32 v144, 1.0
	v_mov_b32_e32 v145, 1.0
	v_mov_b32_e32 v146, 1.0
	v_mov_b32_e32 v147, 1.0
	v_mov_b32_e32 v148, 1.0
	v_mov_b32_e32 v149, 1.0
	v_mov_b32_e32 v150, 1.0
	v_mov_b32_e32 v151, 1.0
	v_mov_b32_e32 v152, 1.0
	v_mov_b32_e32 v153, 1.0
	v_mov_b32_e32 v154, 1.0
	v_mov_b32_e32 v155, 1.0
	v_mov_b32_e32 v156, 1.0
	v_mov_b32_e32 v157, 1.0
	v_mov_b32_e32 v158, 1.0
	v_mov_b32_e32 v159, 1.0
	s_andn2_b64 vcc, exec, s[18:19]
	s_cbranch_vccnz .Lgw1_nog
	v_lshl_add_u64 v[162:163], s[14:15], 0, v[2:3]
	v_lshl_add_u64 v[164:165], s[14:15], 0, v[26:27]
	global_load_dword v128, v[162:163], off
	global_load_dword v129, v[164:165], off offset:8
	global_load_dword v130, v[164:165], off offset:16
	global_load_dword v131, v[164:165], off offset:24
	global_load_dword v132, v[164:165], off offset:32
	global_load_dword v133, v[164:165], off offset:40
	global_load_dword v134, v[164:165], off offset:48
	global_load_dword v135, v[164:165], off offset:56
	global_load_dword v136, v[162:163], off offset:64
	global_load_dword v137, v[164:165], off offset:72
	global_load_dword v138, v[164:165], off offset:80
	global_load_dword v139, v[164:165], off offset:88
	global_load_dword v140, v[164:165], off offset:96
	global_load_dword v141, v[164:165], off offset:104
	global_load_dword v142, v[164:165], off offset:112
	global_load_dword v143, v[164:165], off offset:120
	global_load_dword v144, v[162:163], off offset:128
	global_load_dword v145, v[164:165], off offset:136
	global_load_dword v146, v[164:165], off offset:144
	global_load_dword v147, v[164:165], off offset:152
	global_load_dword v148, v[164:165], off offset:160
	global_load_dword v149, v[164:165], off offset:168
	global_load_dword v150, v[164:165], off offset:176
	global_load_dword v151, v[164:165], off offset:184
	global_load_dword v152, v[162:163], off offset:192
	global_load_dword v153, v[164:165], off offset:200
	global_load_dword v154, v[164:165], off offset:208
	global_load_dword v155, v[164:165], off offset:216
	global_load_dword v156, v[164:165], off offset:224
	global_load_dword v157, v[164:165], off offset:232
	global_load_dword v158, v[164:165], off offset:240
	global_load_dword v159, v[164:165], off offset:248
; #define LAS __attribute__((address_space(3)))
; __device__ __forceinline__ void transpose_item(const float* W, int N, int k0, int n0, bf16_t* dst, int ldd, LAS float* scr, int lane, const float* gk = nullptr) {
; #pragma unroll 8
;     for (int i = 0; i < 32; ++i) { const int kk = 2 * i + (lane >> 5); scr[kk * 33 + (lane & 31)] = W[(size_t)(k0 + kk) * N + n0 + (lane & 31)] * (gk ? gk[k0 + kk] : 1.0f); }
;     asm volatile("s_waitcnt lgkmcnt(0)" ::: "memory");
; __global__ void __launch_bounds__(512, 2) fwd_mega(Args args) {
;     ...
;             if (r < I_UP) { const int kb = r / 176, nb = r % 176, n0 = 32 * nb; const int bj = n0 / DFF, ch = n0 % DFF; const int drow = (ch >> 7) * 256 + bj * 128 + (ch & 127);
;                 transpose_item(w_up + (size_t)l * DM * UPW, UPW, 64 * kb, n0, (bf16_t*)(wl + W_UP) + (size_t)drow * 1024, 1024, scr, lane, ln2 + (size_t)l * DM); continue; }
.Lgw1_nog:
	s_waitcnt vmcnt(0)
	v_mul_f32_e32 v96, v96, v128
	ds_write_b32 v21, v96
	v_mul_f32_e32 v97, v97, v129
	ds_write_b32 v21, v97 offset:264
	v_mul_f32_e32 v98, v98, v130
	ds_write_b32 v21, v98 offset:528
	v_mul_f32_e32 v99, v99, v131
	ds_write_b32 v21, v99 offset:792
	v_mul_f32_e32 v100, v100, v132
	ds_write_b32 v21, v100 offset:1056
	v_mul_f32_e32 v101, v101, v133
	ds_write_b32 v21, v101 offset:1320
	v_mul_f32_e32 v102, v102, v134
	ds_write_b32 v21, v102 offset:1584
	v_mul_f32_e32 v103, v103, v135
	ds_write_b32 v21, v103 offset:1848
	v_mul_f32_e32 v104, v104, v136
	ds_write_b32 v21, v104 offset:2112
	v_mul_f32_e32 v105, v105, v137
	ds_write_b32 v21, v105 offset:2376
	v_mul_f32_e32 v106, v106, v138
	ds_write_b32 v21, v106 offset:2640
	v_mul_f32_e32 v107, v107, v139
	ds_write_b32 v21, v107 offset:2904
	v_mul_f32_e32 v108, v108, v140
	ds_write_b32 v21, v108 offset:3168
	v_mul_f32_e32 v109, v109, v141
	ds_write_b32 v21, v109 offset:3432
	v_mul_f32_e32 v110, v110, v142
	ds_write_b32 v21, v110 offset:3696
	v_mul_f32_e32 v111, v111, v143
	ds_write_b32 v21, v111 offset:3960
	v_mul_f32_e32 v112, v112, v144
	ds_write_b32 v21, v112 offset:4224
	v_mul_f32_e32 v113, v113, v145
	ds_write_b32 v21, v113 offset:4488
	v_mul_f32_e32 v114, v114, v146
	ds_write_b32 v21, v114 offset:4752
	v_mul_f32_e32 v115, v115, v147
	ds_write_b32 v21, v115 offset:5016
	v_mul_f32_e32 v116, v116, v148
	ds_write_b32 v21, v116 offset:5280
	v_mul_f32_e32 v117, v117, v149
	ds_write_b32 v21, v117 offset:5544
	v_mul_f32_e32 v118, v118, v150
	ds_write_b32 v21, v118 offset:5808
	v_mul_f32_e32 v119, v119, v151
	ds_write_b32 v21, v119 offset:6072
	v_mul_f32_e32 v120, v120, v152
	ds_write_b32 v21, v120 offset:6336
	v_mul_f32_e32 v121, v121, v153
	ds_write_b32 v21, v121 offset:6600
	v_mul_f32_e32 v122, v122, v154
	ds_write_b32 v21, v122 offset:6864
	v_mul_f32_e32 v123, v123, v155
	ds_write_b32 v21, v123 offset:7128
	v_mul_f32_e32 v124, v124, v156
	ds_write_b32 v21, v124 offset:7392
	v_mul_f32_e32 v125, v125, v157
	ds_write_b32 v21, v125 offset:7656
	v_mul_f32_e32 v126, v126, v158
	ds_write_b32 v21, v126 offset:7920
	v_mul_f32_e32 v127, v127, v159
	ds_write_b32 v21, v127 offset:8184
	v_add_u32_e32 v21, 0x2100, v21
	s_add_u32 s16, s16, 0x160000
	s_addc_u32 s17, s17, 0
	s_add_u32 s14, s14, 0x100
	s_addc_u32 s15, s15, 0
	s_branch .LBB0_37

; #define LAS __attribute__((address_space(3)))
; #define ln1 (karg(6))
; #define w_in (karg(7))
; __device__ __forceinline__ void transpose_item(const float* W, int N, int k0, int n0, bf16_t* dst, int ldd, LAS float* scr, int lane, const float* gk = nullptr) {
; #pragma unroll 8
;     for (int i = 0; i < 32; ++i) { const int kk = 2 * i + (lane >> 5); scr[kk * 33 + (lane & 31)] = W[(size_t)(k0 + kk) * N + n0 + (lane & 31)] * (gk ? gk[k0 + kk] : 1.0f); }
;     asm volatile("s_waitcnt lgkmcnt(0)" ::: "memory");
; __global__ void __launch_bounds__(512, 2) fwd_mega(Args args) {
;     ...
;             if (r < I_IN) { const int kb = r / 96, nb = r % 96, n0 = 32 * nb; const int drow = n0 < 1024 ? n0 : (n0 < 1536 ? 2560 + n0 - 1024 : (n0 < 2048 ? n0 - 512 : (n0 < 2560 ? 1536 + ((n0 - 2048) >> 7) * 256 + ((n0 - 2048) & 127) : 1536 + ((n0 - 2560) >> 7) * 256 + 128 + ((n0 - 2560) & 127))));
;                 transpose_item(w_in + (size_t)l * DM * PROJ, PROJ, 64 * kb, n0, (bf16_t*)(wl + W_IN) + (size_t)drow * 1024, 1024, scr, lane, ln1 + (size_t)l * DM); continue; }
.LBB0_58:
.LBB0_59:
	v_lshl_add_u64 v[160:161], v[40:41], 0, s[18:19]
	global_load_dword v96, v[160:161], off
	v_lshl_add_u64 v[160:161], v[38:39], 0, s[18:19]
	global_load_dword v97, v[160:161], off
	v_lshl_add_u64 v[160:161], v[36:37], 0, s[18:19]
	global_load_dword v98, v[160:161], off
	v_lshl_add_u64 v[160:161], v[34:35], 0, s[18:19]
	global_load_dword v99, v[160:161], off
	v_lshl_add_u64 v[160:161], v[32:33], 0, s[18:19]
	global_load_dword v100, v[160:161], off
	v_lshl_add_u64 v[160:161], v[30:31], 0, s[18:19]
	global_load_dword v101, v[160:161], off
	v_lshl_add_u64 v[160:161], v[28:29], 0, s[18:19]
	global_load_dword v102, v[160:161], off
	v_lshl_add_u64 v[160:161], v[24:25], 0, s[18:19]
	global_load_dword v103, v[160:161], off
	s_add_u32 s98, s18, 0x30000
	s_addc_u32 s99, s19, 0
	v_lshl_add_u64 v[160:161], v[40:41], 0, s[98:99]
	global_load_dword v104, v[160:161], off
	v_lshl_add_u64 v[160:161], v[38:39], 0, s[98:99]
	global_load_dword v105, v[160:161], off
	v_lshl_add_u64 v[160:161], v[36:37], 0, s[98:99]
	global_load_dword v106, v[160:161], off
	v_lshl_add_u64 v[160:161], v[34:35], 0, s[98:99]
	global_load_dword v107, v[160:161], off
	v_lshl_add_u64 v[160:161], v[32:33], 0, s[98:99]
	global_load_dword v108, v[160:161], off
	v_lshl_add_u64 v[160:161], v[30:31], 0, s[98:99]
	global_load_dword v109, v[160:161], off
	v_lshl_add_u64 v[160:161], v[28:29], 0, s[98:99]
	global_load_dword v110, v[160:161], off
	v_lshl_add_u64 v[160:161], v[24:25], 0, s[98:99]
	global_load_dword v111, v[160:161], off
	s_add_u32 s98, s18, 0x60000
	s_addc_u32 s99, s19, 0
	v_lshl_add_u64 v[160:161], v[40:41], 0, s[98:99]
	global_load_dword v112, v[160:161], off
	v_lshl_add_u64 v[160:161], v[38:39], 0, s[98:99]
	global_load_dword v113, v[160:161], off
	v_lshl_add_u64 v[160:161], v[36:37], 0, s[98:99]
	global_load_dword v114, v[160:161], off
	v_lshl_add_u64 v[160:161], v[34:35], 0, s[98:99]
	global_load_dword v115, v[160:161], off
	v_lshl_add_u64 v[160:161], v[32:33], 0, s[98:99]
	global_load_dword v116, v[160:161], off
	v_lshl_add_u64 v[160:161], v[30:31], 0, s[98:99]
	global_load_dword v117, v[160:161], off
	v_lshl_add_u64 v[160:161], v[28:29], 0, s[98:99]
	global_load_dword v118, v[160:161], off
	v_lshl_add_u64 v[160:161], v[24:25], 0, s[98:99]
	global_load_dword v119, v[160:161], off
	s_add_u32 s98, s18, 0x90000
	s_addc_u32 s99, s19, 0
	v_lshl_add_u64 v[160:161], v[40:41], 0, s[98:99]
	global_load_dword v120, v[160:161], off
	v_lshl_add_u64 v[160:161], v[38:39], 0, s[98:99]
	global_load_dword v121, v[160:161], off
	v_lshl_add_u64 v[160:161], v[36:37], 0, s[98:99]
	global_load_dword v122, v[160:161], off
	v_lshl_add_u64 v[160:161], v[34:35], 0, s[98:99]
	global_load_dword v123, v[160:161], off
	v_lshl_add_u64 v[160:161], v[32:33], 0, s[98:99]
	global_load_dword v124, v[160:161], off
	v_lshl_add_u64 v[160:161], v[30:31], 0, s[98:99]
	global_load_dword v125, v[160:161], off
	v_lshl_add_u64 v[160:161], v[28:29], 0, s[98:99]
	global_load_dword v126, v[160:161], off
	v_lshl_add_u64 v[160:161], v[24:25], 0, s[98:99]
	global_load_dword v127, v[160:161], off
	v_mov_b32_e32 v128, 1.0
	v_mov_b32_e32 v129, 1.0
	v_mov_b32_e32 v130, 1.0
	v_mov_b32_e32 v131, 1.0
	v_mov_b32_e32 v132, 1.0
	v_mov_b32_e32 v133, 1.0
	v_mov_b32_e32 v134, 1.0
	v_mov_b32_e32 v135, 1.0
	v_mov_b32_e32 v136, 1.0
	v_mov_b32_e32 v137, 1.0
	v_mov_b32_e32 v138, 1.0
	v_mov_b32_e32 v139, 1.0
	v_mov_b32_e32 v140, 1.0
	v_mov_b32_e32 v141, 1.0
	v_mov_b32_e32 v142, 1.0
	v_mov_b32_e32 v143, 1.0
	v_mov_b32_e32 v144, 1.0
	v_mov_b32_e32 v145, 1.0
	v_mov_b32_e32 v146, 1.0
	v_mov_b32_e32 v147, 1.0
	v_mov_b32_e32 v148, 1.0
	v_mov_b32_e32 v149, 1.0
	v_mov_b32_e32 v150, 1.0
	v_mov_b32_e32 v151, 1.0
	v_mov_b32_e32 v152, 1.0
	v_mov_b32_e32 v153, 1.0
	v_mov_b32_e32 v154, 1.0
	v_mov_b32_e32 v155, 1.0
	v_mov_b32_e32 v156, 1.0
	v_mov_b32_e32 v157, 1.0
	v_mov_b32_e32 v158, 1.0
	v_mov_b32_e32 v159, 1.0
	s_andn2_b64 vcc, exec, s[20:21]
	s_cbranch_vccnz .Lgw2_nog
	v_lshl_add_u64 v[162:163], s[12:13], 0, v[42:43]
	v_lshl_add_u64 v[164:165], s[12:13], 0, v[26:27]
	global_load_dword v128, v[162:163], off
	global_load_dword v129, v[164:165], off offset:8
	global_load_dword v130, v[164:165], off offset:16
	global_load_dword v131, v[164:165], off offset:24
	global_load_dword v132, v[164:165], off offset:32
	global_load_dword v133, v[164:165], off offset:40
	global_load_dword v134, v[164:165], off offset:48
	global_load_dword v135, v[164:165], off offset:56
	global_load_dword v136, v[162:163], off offset:64
	global_load_dword v137, v[164:165], off offset:72
	global_load_dword v138, v[164:165], off offset:80
	global_load_dword v139, v[164:165], off offset:88
	global_load_dword v140, v[164:165], off offset:96
	global_load_dword v141, v[164:165], off offset:104
	global_load_dword v142, v[164:165], off offset:112
	global_load_dword v143, v[164:165], off offset:120
	global_load_dword v144, v[162:163], off offset:128
	global_load_dword v145, v[164:165], off offset:136
	global_load_dword v146, v[164:165], off offset:144
	global_load_dword v147, v[164:165], off offset:152
	global_load_dword v148, v[164:165], off offset:160
	global_load_dword v149, v[164:165], off offset:168
	global_load_dword v150, v[164:165], off offset:176
	global_load_dword v151, v[164:165], off offset:184
	global_load_dword v152, v[162:163], off offset:192
	global_load_dword v153, v[164:165], off offset:200
	global_load_dword v154, v[164:165], off offset:208
	global_load_dword v155, v[164:165], off offset:216
	global_load_dword v156, v[164:165], off offset:224
	global_load_dword v157, v[164:165], off offset:232
	global_load_dword v158, v[164:165], off offset:240
	global_load_dword v159, v[164:165], off offset:248
; #define LAS __attribute__((address_space(3)))
; #define ln1 (karg(6))
; #define w_in (karg(7))
; __device__ __forceinline__ void transpose_item(const float* W, int N, int k0, int n0, bf16_t* dst, int ldd, LAS float* scr, int lane, const float* gk = nullptr) {
; #pragma unroll 8
;     for (int i = 0; i < 32; ++i) { const int kk = 2 * i + (lane >> 5); scr[kk * 33 + (lane & 31)] = W[(size_t)(k0 + kk) * N + n0 + (lane & 31)] * (gk ? gk[k0 + kk] : 1.0f); }
;     asm volatile("s_waitcnt lgkmcnt(0)" ::: "memory");
; __global__ void __launch_bounds__(512, 2) fwd_mega(Args args) {
;     ...
;             if (r < I_IN) { const int kb = r / 96, nb = r % 96, n0 = 32 * nb; const int drow = n0 < 1024 ? n0 : (n0 < 1536 ? 2560 + n0 - 1024 : (n0 < 2048 ? n0 - 512 : (n0 < 2560 ? 1536 + ((n0 - 2048) >> 7) * 256 + ((n0 - 2048) & 127) : 1536 + ((n0 - 2560) >> 7) * 256 + 128 + ((n0 - 2560) & 127))));
;                 transpose_item(w_in + (size_t)l * DM * PROJ, PROJ, 64 * kb, n0, (bf16_t*)(wl + W_IN) + (size_t)drow * 1024, 1024, scr, lane, ln1 + (size_t)l * DM); continue; }
.Lgw2_nog:
	s_waitcnt vmcnt(0)
	v_mul_f32_e32 v96, v96, v128
	ds_write_b32 v2, v96
	v_mul_f32_e32 v97, v97, v129
	ds_write_b32 v2, v97 offset:264
	v_mul_f32_e32 v98, v98, v130
	ds_write_b32 v2, v98 offset:528
	v_mul_f32_e32 v99, v99, v131
	ds_write_b32 v2, v99 offset:792
	v_mul_f32_e32 v100, v100, v132
	ds_write_b32 v2, v100 offset:1056
	v_mul_f32_e32 v101, v101, v133
	ds_write_b32 v2, v101 offset:1320
	v_mul_f32_e32 v102, v102, v134
	ds_write_b32 v2, v102 offset:1584
	v_mul_f32_e32 v103, v103, v135
	ds_write_b32 v2, v103 offset:1848
	v_mul_f32_e32 v104, v104, v136
	ds_write_b32 v2, v104 offset:2112
	v_mul_f32_e32 v105, v105, v137
	ds_write_b32 v2, v105 offset:2376
	v_mul_f32_e32 v106, v106, v138
	ds_write_b32 v2, v106 offset:2640
	v_mul_f32_e32 v107, v107, v139
	ds_write_b32 v2, v107 offset:2904
	v_mul_f32_e32 v108, v108, v140
	ds_write_b32 v2, v108 offset:3168
	v_mul_f32_e32 v109, v109, v141
	ds_write_b32 v2, v109 offset:3432
	v_mul_f32_e32 v110, v110, v142
	ds_write_b32 v2, v110 offset:3696
	v_mul_f32_e32 v111, v111, v143
	ds_write_b32 v2, v111 offset:3960
	v_mul_f32_e32 v112, v112, v144
	ds_write_b32 v2, v112 offset:4224
	v_mul_f32_e32 v113, v113, v145
	ds_write_b32 v2, v113 offset:4488
	v_mul_f32_e32 v114, v114, v146
	ds_write_b32 v2, v114 offset:4752
	v_mul_f32_e32 v115, v115, v147
	ds_write_b32 v2, v115 offset:5016
	v_mul_f32_e32 v116, v116, v148
	ds_write_b32 v2, v116 offset:5280
	v_mul_f32_e32 v117, v117, v149
	ds_write_b32 v2, v117 offset:5544
	v_mul_f32_e32 v118, v118, v150
	ds_write_b32 v2, v118 offset:5808
	v_mul_f32_e32 v119, v119, v151
	ds_write_b32 v2, v119 offset:6072
	v_mul_f32_e32 v120, v120, v152
	ds_write_b32 v2, v120 offset:6336
	v_mul_f32_e32 v121, v121, v153
	ds_write_b32 v2, v121 offset:6600
	v_mul_f32_e32 v122, v122, v154
	ds_write_b32 v2, v122 offset:6864
	v_mul_f32_e32 v123, v123, v155
	ds_write_b32 v2, v123 offset:7128
	v_mul_f32_e32 v124, v124, v156
	ds_write_b32 v2, v124 offset:7392
	v_mul_f32_e32 v125, v125, v157
	ds_write_b32 v2, v125 offset:7656
	v_mul_f32_e32 v126, v126, v158
	ds_write_b32 v2, v126 offset:7920
	v_mul_f32_e32 v127, v127, v159
	ds_write_b32 v2, v127 offset:8184
	v_add_u32_e32 v2, 0x2100, v2
	s_add_u32 s18, s18, 0xc0000
	s_addc_u32 s19, s19, 0
	s_add_u32 s12, s12, 0x100
	s_addc_u32 s13, s13, 0
	s_branch .LBB0_9
